# P5 output published write-through (sc1 stores) and the barrier behind P5 without the release L2 write-back
# baseline (speedup 1.0000x reference)
;     __device__ __forceinline__ const char* a(const Unit& u) const { return (const char*)A + (size_t)u.pm * 2 * hA(); }
;     __device__ __forceinline__ const char* b(const Unit& u) const { return (const char*)Bt + (size_t)u.pn * 2 * hB() + (size_t)(u.pm >> gshift) * goff; }
;     __device__ __forceinline__ const char* a(const Unit& u) const { return (const char*)A + (size_t)u.pm * 2 * hA(); }
;     __device__ __forceinline__ const char* b(const Unit& u) const { return (const char*)Bt + (size_t)((u.pn >> 4) * 4096 + (u.pn & 15) * 16) * 1024 * 2 + (size_t)(u.pm >> 1) * 512; }
;     __device__ __forceinline__ void operator()(const f32x4 (&acc)[2][2][4][2], const Unit& u, int wr, int wc, int fr, int fq) const {
;     ...
;         float rsv[2][4];
; #pragma unroll
;         for (int ai = 0; ai < 2; ++ai)
; #pragma unroll
;             for (int m = 0; m < 4; ++m) rsv[ai][m] = RS ? rs[row0 + ai * HALF + m * 16] : 1.0f;
; #pragma unroll
;         for (int ai = 0; ai < 2; ++ai)
; #pragma unroll
;             for (int m = 0; m < 4; ++m) { const int r = row0 + ai * HALF + m * 16;
;                 bf16_t* rowp = hm ? base + ((size_t)((r >> 12) * 8 + (colt >> 7)) * 4096 + (r & 4095)) * 128 + wc * 32 + 8 * fq : base + (size_t)r * ldc + col0;
;                 float rv = sc; if (RS == 1) rv *= rsv[ai][m]; if (RS == 2) rv *= __builtin_amdgcn_rsqf(rsv[ai][m] * (1.0f / DM) + EPS);
; #pragma unroll
;                 for (int bj = 0; bj < 2; ++bj) { f32x4 v0 = acc[ai][bj][m][0] * rv, v1 = acc[ai][bj][m][1] * rv;
;                     if (CS) { v0 = v0 * cv[bj][0]; v1 = v1 * cv[bj][1]; }
;                     if (ACT == 2) {
; #pragma unroll
;                         for (int e = 0; e < 4; ++e) { float a = v0[e] > 0.f ? v0[e] : 0.f, b = v1[e] > 0.f ? v1[e] : 0.f; v0[e] = a * a; v1[e] = b * b; } }
;                     if (k8) {
;                         u32x2 w8; w8.x = pk_fp8x4(v0); w8.y = pk_fp8x4(v1);
;                         *(u32x2*)((unsigned char*)base + ((size_t)((r >> 12) * 8 + (colt >> 7) + bj) * 4096 + (r & 4095)) * 128 + wc * 32 + 8 * fq) = w8;
;                     } else {
;                     u32x4 w; w.x = cvt_pk_bf16(v0[0], v0[1]); w.y = cvt_pk_bf16(v0[2], v0[3]); w.z = cvt_pk_bf16(v1[0], v1[1]); w.w = cvt_pk_bf16(v1[2], v1[3]);
;                     *(u32x4*)(rowp + bj * bstep) = w; } } }
.LBB0_719:
	s_mov_b32 s21, s70
	s_lshl_b32 s22, s74, 8
	v_mbcnt_lo_u32_b32 v133, s21, 0
	v_mbcnt_hi_u32_b32 v133, s21, v133
	s_add_i32 s22, s22, s48
	s_lshl_b32 s21, s75, 8
	v_and_or_b32 v134, v133, 15, s22
	v_ashrrev_i32_e32 v135, 31, v134
	v_lshl_add_u64 v[138:139], v[134:135], 2, s[24:25]
	v_mov_b32_e32 v150, v240
	v_mov_b32_e32 v151, v241
	v_mov_b32_e32 v148, v242
	v_ashrrev_i32_e32 v133, 1, v133
	v_and_b32_e32 v149, -8, v133
	v_mov_b32_e32 v147, v243
	v_mov_b32_e32 v146, v244
	v_mov_b32_e32 v145, v245
	v_mov_b32_e32 v144, v246
	v_mov_b32_e32 v133, v247
	s_cmp_lg_u64 s[40:41], 0
	s_cselect_b32 s98, s36, s74
	s_lshl_b32 s98, s98, 8
	s_add_i32 s98, s98, s48
	v_and_or_b32 v248, v134, 15, s98
	v_mov_b32_e32 v249, 0
	v_lshl_add_u64 v[248:249], v[248:249], 2, s[24:25]
	global_load_dword v240, v[248:249], off
	global_load_dword v241, v[248:249], off offset:64
	global_load_dword v242, v[248:249], off offset:128
	global_load_dword v243, v[248:249], off offset:192
	global_load_dword v244, v[248:249], off offset:512
	global_load_dword v245, v[248:249], off offset:576
	global_load_dword v246, v[248:249], off offset:640
	global_load_dword v247, v[248:249], off offset:704
	s_or_b32 s21, s21, s50
	v_add_u32_e32 v138, s21, v149
	v_ashrrev_i32_e32 v139, 31, v138
	v_or_b32_e32 v142, 16, v134
	v_or_b32_e32 v140, 32, v134
	v_or_b32_e32 v136, 48, v134
	v_lshl_add_u64 v[138:139], v[138:139], 1, s[76:77]
	v_lshlrev_b64 v[134:135], 14, v[134:135]
	v_lshl_add_u64 v[134:135], v[138:139], 0, v[134:135]
	v_ashrrev_i32_e32 v143, 31, v142
	v_ashrrev_i32_e32 v141, 31, v140
	v_ashrrev_i32_e32 v137, 31, v136
	s_mov_b32 s21, 0x200000
	s_mov_b64 s[22:23], 0x200000
	v_fmamk_f32 v149, v150, 0x3a000000, v227
	v_rsq_f32_e32 v150, v149
	s_nop 0
	v_pk_mul_f32 v[120:121], v[120:121], v[150:151] op_sel_hi:[1,0]
	v_pk_mul_f32 v[124:125], v[124:125], v[150:151] op_sel_hi:[1,0]
	v_pk_mul_f32 v[122:123], v[122:123], v[150:151] op_sel_hi:[1,0]
	v_max_f32_e32 v120, 0, v120
	v_pk_mul_f32 v[126:127], v[126:127], v[150:151] op_sel_hi:[1,0]
	v_mul_f32_e32 v149, v120, v120
	v_max_f32_e32 v120, 0, v125
	v_max_f32_e32 v121, 0, v121
	v_max_f32_e32 v122, 0, v122
	v_max_f32_e32 v124, 0, v124
	v_mul_f32_e32 v120, v120, v120
	v_mul_f32_e32 v125, v121, v121
	v_max_f32_e32 v121, 0, v126
	v_mul_f32_e32 v126, v122, v122
	v_max_f32_e32 v122, 0, v127
	v_max_f32_e32 v123, 0, v123
	v_pk_mul_f32 v[114:115], v[114:115], v[150:151] op_sel_hi:[1,0]
	v_pk_mul_f32 v[112:113], v[112:113], v[150:151] op_sel_hi:[1,0]
	v_mul_f32_e32 v124, v124, v124
	v_mul_f32_e32 v121, v121, v121
	v_mul_f32_e32 v122, v122, v122
	v_mul_f32_e32 v123, v123, v123
	v_cvt_pk_bf16_f32 v120, v124, v120
	v_pk_mul_f32 v[118:119], v[118:119], v[150:151] op_sel_hi:[1,0]
	v_pk_mul_f32 v[116:117], v[116:117], v[150:151] op_sel_hi:[1,0]
	v_max_f32_e32 v112, 0, v112
	v_max_f32_e32 v113, 0, v113
	v_max_f32_e32 v114, 0, v114
	v_cvt_pk_bf16_f32 v121, v121, v122
	v_cvt_pk_bf16_f32 v122, v149, v125
	v_cvt_pk_bf16_f32 v123, v126, v123
	global_store_dwordx4 v[134:135], v[120:123], off sc1
	v_max_f32_e32 v116, 0, v116
	v_max_f32_e32 v115, 0, v115
	v_mul_f32_e32 v120, v112, v112
	v_max_f32_e32 v112, 0, v117
	v_mul_f32_e32 v117, v113, v113
	v_max_f32_e32 v113, 0, v118
	v_mul_f32_e32 v118, v114, v114
	v_max_f32_e32 v114, 0, v119
	v_mul_f32_e32 v112, v112, v112
	v_mul_f32_e32 v113, v113, v113
	v_mul_f32_e32 v114, v114, v114
	v_mul_f32_e32 v116, v116, v116
	v_mul_f32_e32 v115, v115, v115
	v_cvt_pk_bf16_f32 v112, v116, v112
	v_cvt_pk_bf16_f32 v113, v113, v114
	v_cvt_pk_bf16_f32 v114, v120, v117
	v_cvt_pk_bf16_f32 v115, v118, v115
	global_store_dwordx4 v[134:135], v[112:115], off offset:256 sc1
	s_nop 1
	v_fmamk_f32 v114, v151, 0x3a000000, v227
	v_rsq_f32_e32 v114, v114
	v_lshlrev_b64 v[112:113], 14, v[142:143]
	v_lshl_add_u64 v[112:113], v[138:139], 0, v[112:113]
	v_pk_mul_f32 v[104:105], v[104:105], v[114:115] op_sel_hi:[1,0]
	v_pk_mul_f32 v[108:109], v[108:109], v[114:115] op_sel_hi:[1,0]
	v_pk_mul_f32 v[106:107], v[106:107], v[114:115] op_sel_hi:[1,0]
	v_max_f32_e32 v104, 0, v104
	v_pk_mul_f32 v[110:111], v[110:111], v[114:115] op_sel_hi:[1,0]
	v_mul_f32_e32 v115, v104, v104
	v_max_f32_e32 v104, 0, v109
	v_max_f32_e32 v105, 0, v105
	v_max_f32_e32 v106, 0, v106
	v_max_f32_e32 v108, 0, v108
	v_mul_f32_e32 v104, v104, v104
	v_mul_f32_e32 v109, v105, v105
	v_max_f32_e32 v105, 0, v110
	v_mul_f32_e32 v110, v106, v106
	v_max_f32_e32 v106, 0, v111
	v_max_f32_e32 v107, 0, v107
	v_pk_mul_f32 v[98:99], v[98:99], v[114:115] op_sel_hi:[1,0]
	v_pk_mul_f32 v[96:97], v[96:97], v[114:115] op_sel_hi:[1,0]
	v_mul_f32_e32 v108, v108, v108
	v_mul_f32_e32 v105, v105, v105
	v_mul_f32_e32 v106, v106, v106
	v_mul_f32_e32 v107, v107, v107
	v_cvt_pk_bf16_f32 v104, v108, v104
	v_pk_mul_f32 v[102:103], v[102:103], v[114:115] op_sel_hi:[1,0]
	v_pk_mul_f32 v[100:101], v[100:101], v[114:115] op_sel_hi:[1,0]
	v_max_f32_e32 v96, 0, v96
	v_max_f32_e32 v97, 0, v97
	v_max_f32_e32 v98, 0, v98
	v_cvt_pk_bf16_f32 v105, v105, v106
	v_cvt_pk_bf16_f32 v106, v115, v109
	v_cvt_pk_bf16_f32 v107, v110, v107
	global_store_dwordx4 v[112:113], v[104:107], off sc1
	v_max_f32_e32 v100, 0, v100
	v_max_f32_e32 v99, 0, v99
	v_mul_f32_e32 v104, v96, v96
	v_max_f32_e32 v96, 0, v101
	v_mul_f32_e32 v101, v97, v97
	v_max_f32_e32 v97, 0, v102
	v_mul_f32_e32 v102, v98, v98
	v_max_f32_e32 v98, 0, v103
	v_mul_f32_e32 v96, v96, v96
	v_mul_f32_e32 v97, v97, v97
	v_mul_f32_e32 v98, v98, v98
	v_mul_f32_e32 v100, v100, v100
	v_mul_f32_e32 v99, v99, v99
	v_cvt_pk_bf16_f32 v96, v100, v96
	v_cvt_pk_bf16_f32 v97, v97, v98
	v_cvt_pk_bf16_f32 v98, v104, v101
	v_cvt_pk_bf16_f32 v99, v102, v99
	global_store_dwordx4 v[112:113], v[96:99], off offset:256 sc1
;     __device__ __forceinline__ const char* a(const Unit& u) const { return (const char*)A + (size_t)u.pm * 2 * hA(); }
;     __device__ __forceinline__ const char* b(const Unit& u) const { return (const char*)Bt + (size_t)u.pn * 2 * hB() + (size_t)(u.pm >> gshift) * goff; }
;     __device__ __forceinline__ const char* a(const Unit& u) const { return (const char*)A + (size_t)u.pm * 2 * hA(); }
;     __device__ __forceinline__ const char* b(const Unit& u) const { return (const char*)Bt + (size_t)((u.pn >> 4) * 4096 + (u.pn & 15) * 16) * 1024 * 2 + (size_t)(u.pm >> 1) * 512; }
;     __device__ __forceinline__ const char* a(const Unit&) const { return (const char*)A; }
;     __device__ __forceinline__ const char* b(const Unit& u) const { return (const char*)Bt + ((size_t)(((u.pm >> 4) * 1024 + u.pn * 256) * 16 + (u.pm & 15)) * 512) * 2; }
;     __device__ __forceinline__ void operator()(const f32x4 (&acc)[2][2][4][2], const Unit& u, int wr, int wc, int fr, int fq) const {
;     ...
;         for (int ai = 0; ai < 2; ++ai)
; #pragma unroll
;             for (int m = 0; m < 4; ++m) { const int r = row0 + ai * HALF + m * 16;
;                 bf16_t* rowp = hm ? base + ((size_t)((r >> 12) * 8 + (colt >> 7)) * 4096 + (r & 4095)) * 128 + wc * 32 + 8 * fq : base + (size_t)r * ldc + col0;
;                 float rv = sc; if (RS == 1) rv *= rsv[ai][m]; if (RS == 2) rv *= __builtin_amdgcn_rsqf(rsv[ai][m] * (1.0f / DM) + EPS);
; #pragma unroll
;                 for (int bj = 0; bj < 2; ++bj) { f32x4 v0 = acc[ai][bj][m][0] * rv, v1 = acc[ai][bj][m][1] * rv;
;                     if (CS) { v0 = v0 * cv[bj][0]; v1 = v1 * cv[bj][1]; }
;                     if (ACT == 2) {
; #pragma unroll
;                         for (int e = 0; e < 4; ++e) { float a = v0[e] > 0.f ? v0[e] : 0.f, b = v1[e] > 0.f ? v1[e] : 0.f; v0[e] = a * a; v1[e] = b * b; } }
;                     if (k8) {
;                         u32x2 w8; w8.x = pk_fp8x4(v0); w8.y = pk_fp8x4(v1);
;                         *(u32x2*)((unsigned char*)base + ((size_t)((r >> 12) * 8 + (colt >> 7) + bj) * 4096 + (r & 4095)) * 128 + wc * 32 + 8 * fq) = w8;
;                     } else {
;                     u32x4 w; w.x = cvt_pk_bf16(v0[0], v0[1]); w.y = cvt_pk_bf16(v0[2], v0[3]); w.z = cvt_pk_bf16(v1[0], v1[1]); w.w = cvt_pk_bf16(v1[2], v1[3]);
;                     *(u32x4*)(rowp + bj * bstep) = w; } } }
	s_nop 1
	v_fmamk_f32 v98, v148, 0x3a000000, v227
	v_rsq_f32_e32 v98, v98
	v_lshlrev_b64 v[96:97], 14, v[140:141]
	v_lshl_add_u64 v[96:97], v[138:139], 0, v[96:97]
	v_pk_mul_f32 v[88:89], v[88:89], v[98:99] op_sel_hi:[1,0]
	v_pk_mul_f32 v[92:93], v[92:93], v[98:99] op_sel_hi:[1,0]
	v_pk_mul_f32 v[90:91], v[90:91], v[98:99] op_sel_hi:[1,0]
	v_max_f32_e32 v88, 0, v88
	v_pk_mul_f32 v[94:95], v[94:95], v[98:99] op_sel_hi:[1,0]
	v_mul_f32_e32 v99, v88, v88
	v_max_f32_e32 v88, 0, v93
	v_max_f32_e32 v89, 0, v89
	v_max_f32_e32 v90, 0, v90
	v_max_f32_e32 v92, 0, v92
	v_mul_f32_e32 v88, v88, v88
	v_mul_f32_e32 v93, v89, v89
	v_max_f32_e32 v89, 0, v94
	v_mul_f32_e32 v94, v90, v90
	v_max_f32_e32 v90, 0, v95
	v_max_f32_e32 v91, 0, v91
	v_pk_mul_f32 v[82:83], v[82:83], v[98:99] op_sel_hi:[1,0]
	v_pk_mul_f32 v[80:81], v[80:81], v[98:99] op_sel_hi:[1,0]
	v_mul_f32_e32 v92, v92, v92
	v_mul_f32_e32 v89, v89, v89
	v_mul_f32_e32 v90, v90, v90
	v_mul_f32_e32 v91, v91, v91
	v_cvt_pk_bf16_f32 v88, v92, v88
	v_pk_mul_f32 v[86:87], v[86:87], v[98:99] op_sel_hi:[1,0]
	v_pk_mul_f32 v[84:85], v[84:85], v[98:99] op_sel_hi:[1,0]
	v_max_f32_e32 v80, 0, v80
	v_max_f32_e32 v81, 0, v81
	v_max_f32_e32 v82, 0, v82
	v_cvt_pk_bf16_f32 v89, v89, v90
	v_cvt_pk_bf16_f32 v90, v99, v93
	v_cvt_pk_bf16_f32 v91, v94, v91
	global_store_dwordx4 v[96:97], v[88:91], off sc1
	v_max_f32_e32 v84, 0, v84
	v_max_f32_e32 v83, 0, v83
	v_mul_f32_e32 v88, v80, v80
	v_max_f32_e32 v80, 0, v85
	v_mul_f32_e32 v85, v81, v81
	v_max_f32_e32 v81, 0, v86
	v_mul_f32_e32 v86, v82, v82
	v_max_f32_e32 v82, 0, v87
	v_mul_f32_e32 v80, v80, v80
	v_mul_f32_e32 v81, v81, v81
	v_mul_f32_e32 v82, v82, v82
	v_mul_f32_e32 v84, v84, v84
	v_mul_f32_e32 v83, v83, v83
	v_cvt_pk_bf16_f32 v80, v84, v80
	v_cvt_pk_bf16_f32 v81, v81, v82
	v_cvt_pk_bf16_f32 v82, v88, v85
	v_cvt_pk_bf16_f32 v83, v86, v83
	global_store_dwordx4 v[96:97], v[80:83], off offset:256 sc1
	s_nop 1
	v_fmamk_f32 v82, v147, 0x3a000000, v227
	v_rsq_f32_e32 v82, v82
	v_lshlrev_b64 v[80:81], 14, v[136:137]
	v_lshl_add_u64 v[80:81], v[138:139], 0, v[80:81]
	v_pk_mul_f32 v[72:73], v[72:73], v[82:83] op_sel_hi:[1,0]
	v_pk_mul_f32 v[76:77], v[76:77], v[82:83] op_sel_hi:[1,0]
	v_pk_mul_f32 v[74:75], v[74:75], v[82:83] op_sel_hi:[1,0]
	v_max_f32_e32 v72, 0, v72
	v_pk_mul_f32 v[78:79], v[78:79], v[82:83] op_sel_hi:[1,0]
	v_mul_f32_e32 v83, v72, v72
	v_max_f32_e32 v72, 0, v77
	v_max_f32_e32 v73, 0, v73
	v_max_f32_e32 v74, 0, v74
	v_max_f32_e32 v76, 0, v76
	v_mul_f32_e32 v72, v72, v72
	v_mul_f32_e32 v77, v73, v73
	v_max_f32_e32 v73, 0, v78
	v_mul_f32_e32 v78, v74, v74
	v_max_f32_e32 v74, 0, v79
	v_max_f32_e32 v75, 0, v75
	v_pk_mul_f32 v[66:67], v[66:67], v[82:83] op_sel_hi:[1,0]
	v_pk_mul_f32 v[64:65], v[64:65], v[82:83] op_sel_hi:[1,0]
	v_mul_f32_e32 v76, v76, v76
	v_mul_f32_e32 v73, v73, v73
	v_mul_f32_e32 v74, v74, v74
	v_mul_f32_e32 v75, v75, v75
	v_cvt_pk_bf16_f32 v72, v76, v72
	v_pk_mul_f32 v[70:71], v[70:71], v[82:83] op_sel_hi:[1,0]
	v_pk_mul_f32 v[68:69], v[68:69], v[82:83] op_sel_hi:[1,0]
	v_max_f32_e32 v64, 0, v64
	v_max_f32_e32 v65, 0, v65
	v_max_f32_e32 v66, 0, v66
	v_cvt_pk_bf16_f32 v73, v73, v74
	v_cvt_pk_bf16_f32 v74, v83, v77
	v_cvt_pk_bf16_f32 v75, v78, v75
	global_store_dwordx4 v[80:81], v[72:75], off sc1
	v_max_f32_e32 v68, 0, v68
	v_max_f32_e32 v67, 0, v67
	v_mul_f32_e32 v72, v64, v64
	v_max_f32_e32 v64, 0, v69
	v_mul_f32_e32 v69, v65, v65
	v_max_f32_e32 v65, 0, v70
	v_mul_f32_e32 v70, v66, v66
	v_max_f32_e32 v66, 0, v71
	v_mul_f32_e32 v64, v64, v64
	v_mul_f32_e32 v65, v65, v65
	v_mul_f32_e32 v66, v66, v66
	v_mul_f32_e32 v68, v68, v68
	v_mul_f32_e32 v67, v67, v67
	v_cvt_pk_bf16_f32 v64, v68, v64
	v_cvt_pk_bf16_f32 v65, v65, v66
	v_cvt_pk_bf16_f32 v66, v72, v69
	v_cvt_pk_bf16_f32 v67, v70, v67
	global_store_dwordx4 v[80:81], v[64:67], off offset:256 sc1
	s_nop 1
	v_fmamk_f32 v66, v146, 0x3a000000, v227
	v_rsq_f32_e32 v66, v66
	v_lshl_add_u64 v[64:65], v[134:135], 0, s[22:23]
	s_mov_b64 s[22:23], 0x240000
	v_pk_mul_f32 v[56:57], v[56:57], v[66:67] op_sel_hi:[1,0]
	v_pk_mul_f32 v[60:61], v[60:61], v[66:67] op_sel_hi:[1,0]
	v_pk_mul_f32 v[58:59], v[58:59], v[66:67] op_sel_hi:[1,0]
	v_max_f32_e32 v56, 0, v56
	v_pk_mul_f32 v[62:63], v[62:63], v[66:67] op_sel_hi:[1,0]
	v_max_f32_e32 v60, 0, v60
	v_mul_f32_e32 v67, v56, v56
	v_max_f32_e32 v56, 0, v61
	v_max_f32_e32 v57, 0, v57
	v_max_f32_e32 v58, 0, v58
	v_mul_f32_e32 v60, v60, v60
	v_mul_f32_e32 v56, v56, v56
	v_mul_f32_e32 v61, v57, v57
	v_max_f32_e32 v57, 0, v62
	v_mul_f32_e32 v62, v58, v58
	v_max_f32_e32 v58, 0, v63
	v_mul_f32_e32 v57, v57, v57
	v_max_f32_e32 v59, 0, v59
	v_mul_f32_e32 v58, v58, v58
	v_cvt_pk_bf16_f32 v56, v60, v56
	v_add_co_u32_e32 v60, vcc, s21, v134
	v_pk_mul_f32 v[50:51], v[50:51], v[66:67] op_sel_hi:[1,0]
	v_pk_mul_f32 v[48:49], v[48:49], v[66:67] op_sel_hi:[1,0]
	v_mul_f32_e32 v59, v59, v59
	v_cvt_pk_bf16_f32 v57, v57, v58
	v_cvt_pk_bf16_f32 v58, v67, v61
	v_addc_co_u32_e32 v61, vcc, 0, v135, vcc
	v_pk_mul_f32 v[54:55], v[54:55], v[66:67] op_sel_hi:[1,0]
	v_pk_mul_f32 v[52:53], v[52:53], v[66:67] op_sel_hi:[1,0]
	v_max_f32_e32 v48, 0, v48
	v_max_f32_e32 v49, 0, v49
	v_max_f32_e32 v50, 0, v50
	v_cvt_pk_bf16_f32 v59, v62, v59
	global_store_dwordx4 v[60:61], v[56:59], off sc1
	v_max_f32_e32 v52, 0, v52
	v_max_f32_e32 v51, 0, v51
	v_mul_f32_e32 v56, v48, v48
	v_max_f32_e32 v48, 0, v53
	v_mul_f32_e32 v53, v49, v49
	v_max_f32_e32 v49, 0, v54
	v_mul_f32_e32 v54, v50, v50
	v_max_f32_e32 v50, 0, v55
	v_mul_f32_e32 v48, v48, v48
	v_mul_f32_e32 v49, v49, v49
	v_mul_f32_e32 v50, v50, v50
	v_mul_f32_e32 v52, v52, v52
	v_mul_f32_e32 v51, v51, v51
	v_cvt_pk_bf16_f32 v48, v52, v48
;     __device__ __forceinline__ const char* a(const Unit& u) const { return (const char*)A + (size_t)u.pm * 2 * hA(); }
;     __device__ __forceinline__ const char* b(const Unit& u) const { return (const char*)Bt + (size_t)u.pn * 2 * hB() + (size_t)(u.pm >> gshift) * goff; }
;     __device__ __forceinline__ const char* a(const Unit& u) const { return (const char*)A + (size_t)u.pm * 2 * hA(); }
; #define PG8_BAR __builtin_amdgcn_s_barrier()
;     __device__ __forceinline__ void operator()(const f32x4 (&acc)[2][2][4][2], const Unit& u, int wr, int wc, int fr, int fq) const {
;     ...
;         for (int ai = 0; ai < 2; ++ai)
; #pragma unroll
;             for (int m = 0; m < 4; ++m) { const int r = row0 + ai * HALF + m * 16;
;                 bf16_t* rowp = hm ? base + ((size_t)((r >> 12) * 8 + (colt >> 7)) * 4096 + (r & 4095)) * 128 + wc * 32 + 8 * fq : base + (size_t)r * ldc + col0;
;                 float rv = sc; if (RS == 1) rv *= rsv[ai][m]; if (RS == 2) rv *= __builtin_amdgcn_rsqf(rsv[ai][m] * (1.0f / DM) + EPS);
; #pragma unroll
;                 for (int bj = 0; bj < 2; ++bj) { f32x4 v0 = acc[ai][bj][m][0] * rv, v1 = acc[ai][bj][m][1] * rv;
;                     if (CS) { v0 = v0 * cv[bj][0]; v1 = v1 * cv[bj][1]; }
;                     if (ACT == 2) {
; #pragma unroll
;                         for (int e = 0; e < 4; ++e) { float a = v0[e] > 0.f ? v0[e] : 0.f, b = v1[e] > 0.f ? v1[e] : 0.f; v0[e] = a * a; v1[e] = b * b; } }
;                     if (k8) {
;                         u32x2 w8; w8.x = pk_fp8x4(v0); w8.y = pk_fp8x4(v1);
;                         *(u32x2*)((unsigned char*)base + ((size_t)((r >> 12) * 8 + (colt >> 7) + bj) * 4096 + (r & 4095)) * 128 + wc * 32 + 8 * fq) = w8;
;                     } else {
;                     u32x4 w; w.x = cvt_pk_bf16(v0[0], v0[1]); w.y = cvt_pk_bf16(v0[2], v0[3]); w.z = cvt_pk_bf16(v1[0], v1[1]); w.w = cvt_pk_bf16(v1[2], v1[3]);
;                     *(u32x4*)(rowp + bj * bstep) = w; } } }
;     ...
;         if (!has_next) break;
; #pragma unroll
;         for (int a = 0; a < 2; ++a)
; #pragma unroll
;             for (int b = 0; b < 2; ++b)
; #pragma unroll
;                 for (int m = 0; m < 4; ++m)
; #pragma unroll
;                     for (int n = 0; n < 2; ++n) acc[a][b][m][n] = (f32x4){0.f, 0.f, 0.f, 0.f};
;         cur = nxt; cA = nA; cB = nB; ++ui;
;         if constexpr (ALIGN_EPI) { if (wr == 1) PG8_BAR; }
	v_cvt_pk_bf16_f32 v49, v49, v50
	v_cvt_pk_bf16_f32 v50, v56, v53
	v_cvt_pk_bf16_f32 v51, v54, v51
	global_store_dwordx4 v[64:65], v[48:51], off offset:256 sc1
	s_mov_b32 s21, 0x240000
	s_nop 0
	v_fmamk_f32 v50, v145, 0x3a000000, v227
	v_rsq_f32_e32 v50, v50
	v_lshl_add_u64 v[48:49], v[134:135], 0, s[22:23]
	s_mov_b64 s[22:23], 0x280000
	v_pk_mul_f32 v[40:41], v[40:41], v[50:51] op_sel_hi:[1,0]
	v_pk_mul_f32 v[44:45], v[44:45], v[50:51] op_sel_hi:[1,0]
	v_pk_mul_f32 v[42:43], v[42:43], v[50:51] op_sel_hi:[1,0]
	v_max_f32_e32 v40, 0, v40
	v_pk_mul_f32 v[46:47], v[46:47], v[50:51] op_sel_hi:[1,0]
	v_max_f32_e32 v44, 0, v44
	v_mul_f32_e32 v51, v40, v40
	v_max_f32_e32 v40, 0, v45
	v_max_f32_e32 v41, 0, v41
	v_max_f32_e32 v42, 0, v42
	v_mul_f32_e32 v44, v44, v44
	v_mul_f32_e32 v40, v40, v40
	v_mul_f32_e32 v45, v41, v41
	v_max_f32_e32 v41, 0, v46
	v_mul_f32_e32 v46, v42, v42
	v_max_f32_e32 v42, 0, v47
	v_mul_f32_e32 v41, v41, v41
	v_max_f32_e32 v43, 0, v43
	v_mul_f32_e32 v42, v42, v42
	v_cvt_pk_bf16_f32 v40, v44, v40
	v_add_co_u32_e32 v44, vcc, s21, v134
	v_pk_mul_f32 v[34:35], v[34:35], v[50:51] op_sel_hi:[1,0]
	v_pk_mul_f32 v[32:33], v[32:33], v[50:51] op_sel_hi:[1,0]
	v_mul_f32_e32 v43, v43, v43
	v_cvt_pk_bf16_f32 v41, v41, v42
	v_cvt_pk_bf16_f32 v42, v51, v45
	v_addc_co_u32_e32 v45, vcc, 0, v135, vcc
	v_pk_mul_f32 v[38:39], v[38:39], v[50:51] op_sel_hi:[1,0]
	v_pk_mul_f32 v[36:37], v[36:37], v[50:51] op_sel_hi:[1,0]
	v_max_f32_e32 v32, 0, v32
	v_max_f32_e32 v33, 0, v33
	v_max_f32_e32 v34, 0, v34
	v_cvt_pk_bf16_f32 v43, v46, v43
	global_store_dwordx4 v[44:45], v[40:43], off sc1
	v_max_f32_e32 v36, 0, v36
	v_max_f32_e32 v35, 0, v35
	v_mul_f32_e32 v40, v32, v32
	v_max_f32_e32 v32, 0, v37
	v_mul_f32_e32 v37, v33, v33
	v_max_f32_e32 v33, 0, v38
	v_mul_f32_e32 v38, v34, v34
	v_max_f32_e32 v34, 0, v39
	v_mul_f32_e32 v32, v32, v32
	v_mul_f32_e32 v33, v33, v33
	v_mul_f32_e32 v34, v34, v34
	v_mul_f32_e32 v36, v36, v36
	v_mul_f32_e32 v35, v35, v35
	v_cvt_pk_bf16_f32 v32, v36, v32
	v_cvt_pk_bf16_f32 v33, v33, v34
	v_cvt_pk_bf16_f32 v34, v40, v37
	v_cvt_pk_bf16_f32 v35, v38, v35
	global_store_dwordx4 v[48:49], v[32:35], off offset:256 sc1
	s_mov_b32 s21, 0x280000
	s_nop 0
	v_fmamk_f32 v34, v144, 0x3a000000, v227
	v_rsq_f32_e32 v34, v34
	v_lshl_add_u64 v[32:33], v[134:135], 0, s[22:23]
	s_mov_b64 s[22:23], 0x2c0000
	v_pk_mul_f32 v[24:25], v[24:25], v[34:35] op_sel_hi:[1,0]
	v_pk_mul_f32 v[28:29], v[28:29], v[34:35] op_sel_hi:[1,0]
	v_pk_mul_f32 v[26:27], v[26:27], v[34:35] op_sel_hi:[1,0]
	v_max_f32_e32 v24, 0, v24
	v_pk_mul_f32 v[30:31], v[30:31], v[34:35] op_sel_hi:[1,0]
	v_max_f32_e32 v28, 0, v28
	v_mul_f32_e32 v35, v24, v24
	v_max_f32_e32 v24, 0, v29
	v_max_f32_e32 v25, 0, v25
	v_max_f32_e32 v26, 0, v26
	v_mul_f32_e32 v28, v28, v28
	v_mul_f32_e32 v24, v24, v24
	v_mul_f32_e32 v29, v25, v25
	v_max_f32_e32 v25, 0, v30
	v_mul_f32_e32 v30, v26, v26
	v_max_f32_e32 v26, 0, v31
	v_mul_f32_e32 v25, v25, v25
	v_max_f32_e32 v27, 0, v27
	v_mul_f32_e32 v26, v26, v26
	v_cvt_pk_bf16_f32 v24, v28, v24
	v_add_co_u32_e32 v28, vcc, s21, v134
	v_pk_mul_f32 v[18:19], v[18:19], v[34:35] op_sel_hi:[1,0]
	v_pk_mul_f32 v[16:17], v[16:17], v[34:35] op_sel_hi:[1,0]
	v_mul_f32_e32 v27, v27, v27
	v_cvt_pk_bf16_f32 v25, v25, v26
	v_cvt_pk_bf16_f32 v26, v35, v29
	v_addc_co_u32_e32 v29, vcc, 0, v135, vcc
	v_pk_mul_f32 v[22:23], v[22:23], v[34:35] op_sel_hi:[1,0]
	v_pk_mul_f32 v[20:21], v[20:21], v[34:35] op_sel_hi:[1,0]
	v_max_f32_e32 v16, 0, v16
	v_max_f32_e32 v17, 0, v17
	v_max_f32_e32 v18, 0, v18
	v_cvt_pk_bf16_f32 v27, v30, v27
	global_store_dwordx4 v[28:29], v[24:27], off sc1
	v_max_f32_e32 v20, 0, v20
	v_max_f32_e32 v19, 0, v19
	v_mul_f32_e32 v24, v16, v16
	v_max_f32_e32 v16, 0, v21
	v_mul_f32_e32 v21, v17, v17
	v_max_f32_e32 v17, 0, v22
	v_mul_f32_e32 v22, v18, v18
	v_max_f32_e32 v18, 0, v23
	v_mul_f32_e32 v16, v16, v16
	v_mul_f32_e32 v17, v17, v17
	v_mul_f32_e32 v18, v18, v18
	v_mul_f32_e32 v20, v20, v20
	v_mul_f32_e32 v19, v19, v19
	v_cvt_pk_bf16_f32 v16, v20, v16
	v_cvt_pk_bf16_f32 v17, v17, v18
	v_cvt_pk_bf16_f32 v18, v24, v21
	v_cvt_pk_bf16_f32 v19, v22, v19
	global_store_dwordx4 v[32:33], v[16:19], off offset:256 sc1
	s_mov_b32 s21, 0x2c0000
	s_nop 0
	v_fmamk_f32 v18, v133, 0x3a000000, v227
	v_rsq_f32_e32 v18, v18
	v_lshl_add_u64 v[16:17], v[134:135], 0, s[22:23]
	s_mov_b64 s[22:23], -1
	v_pk_mul_f32 v[8:9], v[8:9], v[18:19] op_sel_hi:[1,0]
	v_pk_mul_f32 v[12:13], v[12:13], v[18:19] op_sel_hi:[1,0]
	v_pk_mul_f32 v[10:11], v[10:11], v[18:19] op_sel_hi:[1,0]
	v_max_f32_e32 v8, 0, v8
	v_pk_mul_f32 v[14:15], v[14:15], v[18:19] op_sel_hi:[1,0]
	v_max_f32_e32 v12, 0, v12
	v_mul_f32_e32 v19, v8, v8
	v_max_f32_e32 v8, 0, v13
	v_max_f32_e32 v9, 0, v9
	v_max_f32_e32 v10, 0, v10
	v_mul_f32_e32 v12, v12, v12
	v_mul_f32_e32 v8, v8, v8
	v_mul_f32_e32 v13, v9, v9
	v_max_f32_e32 v9, 0, v14
	v_mul_f32_e32 v14, v10, v10
	v_max_f32_e32 v10, 0, v15
	v_mul_f32_e32 v9, v9, v9
	v_max_f32_e32 v11, 0, v11
	v_mul_f32_e32 v10, v10, v10
	v_cvt_pk_bf16_f32 v8, v12, v8
	v_add_co_u32_e32 v12, vcc, s21, v134
	v_pk_mul_f32 v[2:3], v[2:3], v[18:19] op_sel_hi:[1,0]
	v_pk_mul_f32 v[0:1], v[0:1], v[18:19] op_sel_hi:[1,0]
	v_mul_f32_e32 v11, v11, v11
	v_cvt_pk_bf16_f32 v9, v9, v10
	v_cvt_pk_bf16_f32 v10, v19, v13
	v_addc_co_u32_e32 v13, vcc, 0, v135, vcc
	v_pk_mul_f32 v[6:7], v[6:7], v[18:19] op_sel_hi:[1,0]
	v_pk_mul_f32 v[4:5], v[4:5], v[18:19] op_sel_hi:[1,0]
	v_max_f32_e32 v0, 0, v0
	v_max_f32_e32 v1, 0, v1
	v_max_f32_e32 v2, 0, v2
	v_cvt_pk_bf16_f32 v11, v14, v11
	global_store_dwordx4 v[12:13], v[8:11], off sc1
	v_max_f32_e32 v3, 0, v3
	v_max_f32_e32 v4, 0, v4
	v_mul_f32_e32 v8, v0, v0
	v_max_f32_e32 v0, 0, v5
	v_mul_f32_e32 v5, v1, v1
	v_max_f32_e32 v1, 0, v6
	v_mul_f32_e32 v6, v2, v2
	v_max_f32_e32 v2, 0, v7
	v_mul_f32_e32 v0, v0, v0
	v_mul_f32_e32 v1, v1, v1
	v_mul_f32_e32 v2, v2, v2
	v_mul_f32_e32 v3, v3, v3
	s_andn2_b64 vcc, exec, s[40:41]
	v_mul_f32_e32 v4, v4, v4
	v_cvt_pk_bf16_f32 v0, v4, v0
	v_cvt_pk_bf16_f32 v1, v1, v2
	v_cvt_pk_bf16_f32 v2, v8, v5
	v_cvt_pk_bf16_f32 v3, v6, v3
	global_store_dwordx4 v[16:17], v[0:3], off offset:256 sc1
	s_cbranch_vccnz .LBB0_708
	s_and_b64 vcc, exec, s[38:39]
	s_cbranch_vccnz .LBB0_707
	s_barrier
	s_branch .LBB0_707

; __device__ __forceinline__ unsigned xb_add(unsigned* p, unsigned v) { return __hip_atomic_fetch_add(p, v, __ATOMIC_RELAXED, __HIP_MEMORY_SCOPE_AGENT); }
; __device__ __forceinline__ void xcd_barrier(const XcdBarrier& b, const int wave) {
;     ...
;         if (old + 1u == (gen + 1u) * nloc) {
;             __builtin_amdgcn_fence(__ATOMIC_RELEASE, "agent");
;             asm volatile("s_waitcnt vmcnt(0)" ::: "memory");
;             const unsigned og = xb_add(&bar[XB_TOP], 1u);
;             const unsigned tg = og / nx;
;             if (og + 1u == (tg + 1u) * nx) xb_add(&bar[XB_TOPGEN], 1u);
.LBB0_756:
	s_andn2_saveexec_b64 s[0:1], s[22:23]
	s_cbranch_execz .LBB0_776
	s_mov_b64 s[22:23], exec
	s_waitcnt lgkmcnt(0)
	s_waitcnt vmcnt(0)
	v_mbcnt_lo_u32_b32 v1, s22, 0
	v_mbcnt_hi_u32_b32 v1, s23, v1
	v_cmp_eq_u32_e32 vcc, 0, v1
	s_and_saveexec_b64 s[24:25], vcc
	s_cbranch_execz .LBB0_759
	s_bcnt1_i32_b64 s0, s[22:23]
	v_mov_b32_e32 v2, s0
	v_readlane_b32 s0, v255, 14
	v_readlane_b32 s1, v255, 15
	s_nop 4
	global_atomic_add v2, v193, v2, s[0:1] sc0
